# best5 + grid barrier: all workgroups poll the cross-XCD arrival counter until (gen+1)*nXCD; TOPGEN/XGEN relay adds dropped
# speedup vs baseline: 1.0021x; 1.0021x over previous
; __device__ __forceinline__ unsigned xb_ld(unsigned* p)              { return __hip_atomic_load(p, __ATOMIC_RELAXED, __HIP_MEMORY_SCOPE_AGENT); }
; __device__ __forceinline__ unsigned xb_add(unsigned* p, unsigned v) { return __hip_atomic_fetch_add(p, v, __ATOMIC_RELAXED, __HIP_MEMORY_SCOPE_AGENT); }
; #define XB_SPIN(cond, bar) do { unsigned _sp = 0; while (cond) { __builtin_amdgcn_s_sleep(1); \
;     if ((++_sp & 255u) == 0u) { if (xb_ld(&(bar)[XB_TMO])) break; if (_sp > XB_SPIN_CAP) { atomicAdd(&(bar)[XB_TMO], 1u); break; } } } } while (0)
; __device__ __forceinline__ void xcd_barrier(const XcdBarrier& b) {
;     ...
;         const unsigned old = xb_add(&bar[XB_XSUB(b.x)], 1u);
;         const unsigned gen = old / nloc;
;         if (old + 1u == (gen + 1u) * nloc) {
;             __builtin_amdgcn_fence(__ATOMIC_RELEASE, "agent");
;             asm volatile("s_waitcnt vmcnt(0)" ::: "memory");
;             const unsigned og = xb_add(&bar[XB_TOP], 1u);
;             const unsigned tg = og / nx;
;             if (og + 1u == (tg + 1u) * nx) xb_add(&bar[XB_TOPGEN], 1u);
;             else XB_SPIN(xb_ld(&bar[XB_TOPGEN]) == tg, bar);
;             __builtin_amdgcn_fence(__ATOMIC_ACQUIRE, "agent");
;             xb_add(&bar[XB_XGEN(b.x)], 1u);
;             asm volatile("s_waitcnt vmcnt(0)" ::: "memory");
;         } else {
;             XB_SPIN(xb_ld(&bar[XB_XGEN(b.x)]) == gen, bar);
.LBB0_538:
	s_or_b64 exec, exec, s[22:23]
	v_cvt_f32_u32_e32 v4, v2
	s_waitcnt vmcnt(0)
	v_readfirstlane_b32 s0, v3
	v_sub_u32_e32 v3, 0, v2
	v_rcp_iflag_f32_e32 v4, v4
	v_add_u32_e32 v5, s0, v1
	v_mul_f32_e32 v4, 0x4f7ffffe, v4
	v_cvt_u32_f32_e32 v4, v4
	v_mul_lo_u32 v1, v3, v4
	v_mul_hi_u32 v1, v4, v1
	v_add_u32_e32 v1, v4, v1
	v_mul_hi_u32 v1, v5, v1
	v_mul_lo_u32 v3, v1, v2
	v_sub_u32_e32 v3, v5, v3
	v_add_u32_e32 v4, 1, v1
	v_cmp_ge_u32_e32 vcc, v3, v2
	s_nop 1
	v_cndmask_b32_e32 v1, v1, v4, vcc
	v_sub_u32_e32 v4, v3, v2
	v_cndmask_b32_e32 v3, v3, v4, vcc
	v_add_u32_e32 v4, 1, v1
	v_cmp_ge_u32_e32 vcc, v3, v2
	v_add_u32_e32 v3, 1, v5
	s_nop 0
	v_cndmask_b32_e32 v1, v1, v4, vcc
	v_mul_lo_u32 v4, v2, v1
	v_add_u32_e32 v2, v4, v2
	v_cmp_ne_u32_e32 vcc, v3, v2
	s_and_saveexec_b64 s[16:17], vcc
	s_xor_b64 s[22:23], exec, s[16:17]
	s_cbranch_execz .LBB0_553
	v_readlane_b32 s16, v252, 21
	v_readlane_b32 s17, v252, 22
	s_waitcnt lgkmcnt(0)
	v_add_u32_e32 v4, 1, v1
	v_mul_lo_u32 v4, v4, v0
	s_nop 3
	global_load_dword v0, v97, s[16:17] sc1
	s_waitcnt vmcnt(0)
	v_cmp_lt_u32_e32 vcc, v0, v4
	s_and_saveexec_b64 s[38:39], vcc
	s_cbranch_execz .LBB0_552
	s_mov_b32 s0, 1
	s_mov_b64 s[40:41], 0
	s_branch .LBB0_542

; __device__ __forceinline__ unsigned xb_ld(unsigned* p)              { return __hip_atomic_load(p, __ATOMIC_RELAXED, __HIP_MEMORY_SCOPE_AGENT); }
; #define XB_SPIN(cond, bar) do { unsigned _sp = 0; while (cond) { __builtin_amdgcn_s_sleep(1); \
;     if ((++_sp & 255u) == 0u) { if (xb_ld(&(bar)[XB_TMO])) break; if (_sp > XB_SPIN_CAP) { atomicAdd(&(bar)[XB_TMO], 1u); break; } } } } while (0)
; __device__ __forceinline__ void xcd_barrier(const XcdBarrier& b) {
;     ...
;             XB_SPIN(xb_ld(&bar[XB_XGEN(b.x)]) == gen, bar);
.LBB0_544:
	v_readlane_b32 s16, v252, 21
	v_readlane_b32 s17, v252, 22
	s_add_i32 s0, s0, 1
	s_mov_b64 s[46:47], -1
	s_nop 2
	global_load_dword v0, v97, s[16:17] sc1
	s_waitcnt vmcnt(0)
	v_cmp_ge_u32_e32 vcc, v0, v4
	s_orn2_b64 s[44:45], vcc, exec
	s_branch .LBB0_541

; __device__ __forceinline__ unsigned xb_ld(unsigned* p)              { return __hip_atomic_load(p, __ATOMIC_RELAXED, __HIP_MEMORY_SCOPE_AGENT); }
; __device__ __forceinline__ unsigned xb_add(unsigned* p, unsigned v) { return __hip_atomic_fetch_add(p, v, __ATOMIC_RELAXED, __HIP_MEMORY_SCOPE_AGENT); }
; #define XB_SPIN(cond, bar) do { unsigned _sp = 0; while (cond) { __builtin_amdgcn_s_sleep(1); \
;     if ((++_sp & 255u) == 0u) { if (xb_ld(&(bar)[XB_TMO])) break; if (_sp > XB_SPIN_CAP) { atomicAdd(&(bar)[XB_TMO], 1u); break; } } } } while (0)
; __device__ __forceinline__ void xcd_barrier(const XcdBarrier& b) {
;     ...
;             const unsigned og = xb_add(&bar[XB_TOP], 1u);
;             const unsigned tg = og / nx;
;             if (og + 1u == (tg + 1u) * nx) xb_add(&bar[XB_TOPGEN], 1u);
;             else XB_SPIN(xb_ld(&bar[XB_TOPGEN]) == tg, bar);
;             __builtin_amdgcn_fence(__ATOMIC_ACQUIRE, "agent");
.LBB0_556:
	s_or_b64 exec, exec, s[38:39]
	s_waitcnt vmcnt(0)
	v_readfirstlane_b32 s0, v2
	v_cvt_f32_u32_e32 v2, v0
	v_sub_u32_e32 v3, 0, v0
	v_add_u32_e32 v1, s0, v1
	v_readlane_b32 s16, v252, 23
	v_rcp_iflag_f32_e32 v2, v2
	v_readlane_b32 s17, v252, 24
	s_mov_b64 s[38:39], 0
	v_mul_f32_e32 v2, 0x4f7ffffe, v2
	v_cvt_u32_f32_e32 v2, v2
	v_mul_lo_u32 v3, v3, v2
	v_mul_hi_u32 v3, v2, v3
	v_add_u32_e32 v2, v2, v3
	v_mul_hi_u32 v2, v1, v2
	v_mul_lo_u32 v3, v2, v0
	v_sub_u32_e32 v3, v1, v3
	v_cmp_ge_u32_e32 vcc, v3, v0
	v_add_u32_e32 v4, 1, v2
	v_add_u32_e32 v1, 1, v1
	v_cndmask_b32_e32 v2, v2, v4, vcc
	v_sub_u32_e32 v4, v3, v0
	v_cndmask_b32_e32 v3, v3, v4, vcc
	v_cmp_ge_u32_e32 vcc, v3, v0
	v_add_u32_e32 v3, 1, v2
	s_nop 0
	v_cndmask_b32_e32 v2, v2, v3, vcc
	v_mul_lo_u32 v3, v0, v2
	v_add_u32_e32 v0, v3, v0
	v_cmp_ne_u32_e32 vcc, v1, v0
	v_mov_b32_e32 v3, v0
	v_mov_b64_e32 v[0:1], s[16:17]
	s_and_saveexec_b64 s[22:23], vcc
	s_cbranch_execz .LBB0_568
	v_readlane_b32 s16, v252, 21
	v_readlane_b32 s17, v252, 22
	s_mov_b64 s[40:41], 0
	s_nop 3
	global_load_dword v0, v97, s[16:17] sc1
	s_waitcnt vmcnt(0)
	v_cmp_lt_u32_e32 vcc, v0, v3
	s_and_saveexec_b64 s[38:39], vcc
	s_cbranch_execz .LBB0_567
	s_mov_b32 s0, 1
	s_branch .LBB0_560

; __device__ __forceinline__ unsigned xb_ld(unsigned* p)              { return __hip_atomic_load(p, __ATOMIC_RELAXED, __HIP_MEMORY_SCOPE_AGENT); }
; #define XB_SPIN(cond, bar) do { unsigned _sp = 0; while (cond) { __builtin_amdgcn_s_sleep(1); \
;     if ((++_sp & 255u) == 0u) { if (xb_ld(&(bar)[XB_TMO])) break; if (_sp > XB_SPIN_CAP) { atomicAdd(&(bar)[XB_TMO], 1u); break; } } } } while (0)
; __device__ __forceinline__ void xcd_barrier(const XcdBarrier& b) {
;     ...
;             else XB_SPIN(xb_ld(&bar[XB_TOPGEN]) == tg, bar);
.LBB0_562:
	v_readlane_b32 s16, v252, 21
	v_readlane_b32 s17, v252, 22
	s_add_i32 s0, s0, 1
	s_mov_b64 s[46:47], -1
	s_nop 2
	global_load_dword v0, v97, s[16:17] sc1
	s_waitcnt vmcnt(0)
	v_cmp_ge_u32_e32 vcc, v0, v3
	s_orn2_b64 s[44:45], vcc, exec
	s_branch .LBB0_559

; __device__ __forceinline__ unsigned xb_add(unsigned* p, unsigned v) { return __hip_atomic_fetch_add(p, v, __ATOMIC_RELAXED, __HIP_MEMORY_SCOPE_AGENT); }
; __device__ __forceinline__ void xcd_barrier(const XcdBarrier& b) {
;     ...
;             __builtin_amdgcn_fence(__ATOMIC_ACQUIRE, "agent");
;             xb_add(&bar[XB_XGEN(b.x)], 1u);
;             asm volatile("s_waitcnt vmcnt(0)" ::: "memory");
.LBB0_570:
	s_or_b64 exec, exec, s[22:23]
	s_mov_b64 s[22:23], exec
	v_mbcnt_lo_u32_b32 v0, s22, 0
	v_mbcnt_hi_u32_b32 v0, s23, v0
	v_cmp_eq_u32_e32 vcc, 0, v0
	s_waitcnt vmcnt(0)
	buffer_inv sc1
	s_and_saveexec_b64 s[38:39], vcc
	s_cbranch_execz .LBB0_17
	s_bcnt1_i32_b64 s0, s[22:23]
	v_readlane_b32 s16, v252, 19
	v_mov_b32_e32 v0, s0
	v_readlane_b32 s17, v252, 20
	s_nop 4
	s_branch .LBB0_17
